# v18: phase-2 gate stage rewritten by hand: the four 16-token blocks run as four interleaved streams (batched LDS reads, interleaved MFMA chains and log-sigmoid chains, batched shuffles), same operatio
# baseline (speedup 1.0000x reference)
; #define LAS __attribute__((address_space(3)))
; __device__ __forceinline__ void phase_gla_pre(const Params& P, LAS unsigned char* lds, bool dry) {
;     ...
;         __syncthreads();
;         float run = 0.f;
; #pragma unroll
;         for (int tt = 0; tt < 4; ++tt) {
;             bf16x8 ahi = (bf16x8){0, 0, 0, 0, 0, 0, 0, 0}, alo = ahi;
;             if (g < 2) { const f32x4 l0 = *(const LAS f32x4*)(Llr + (16 * tt + fr) * 16 + 8 * g), l1 = *(const LAS f32x4*)(Llr + (16 * tt + fr) * 16 + 8 * g + 4); split8(l0, l1, ahi, alo); }
.Lp2_join:
	s_waitcnt lgkmcnt(0)
	s_barrier
	v_mov_b32_e32 v100, 0
	v_mov_b32_e32 v101, 0
	v_mov_b32_e32 v102, 0
	v_mov_b32_e32 v103, 0
	v_mov_b32_e32 v104, 0
	v_mov_b32_e32 v105, 0
	v_mov_b32_e32 v106, 0
	v_mov_b32_e32 v107, 0
	v_mov_b32_e32 v108, 0
	v_mov_b32_e32 v109, 0
	v_mov_b32_e32 v110, 0
	v_mov_b32_e32 v111, 0
	v_mov_b32_e32 v112, 0
	v_mov_b32_e32 v113, 0
	v_mov_b32_e32 v114, 0
	v_mov_b32_e32 v115, 0
	v_mov_b32_e32 v116, 0
	v_mov_b32_e32 v117, 0
	v_mov_b32_e32 v118, 0
	v_mov_b32_e32 v119, 0
	v_mov_b32_e32 v120, 0
	v_mov_b32_e32 v121, 0
	v_mov_b32_e32 v122, 0
	v_mov_b32_e32 v123, 0
	v_mov_b32_e32 v124, 0
	v_mov_b32_e32 v125, 0
	v_mov_b32_e32 v126, 0
	v_mov_b32_e32 v127, 0
	v_mov_b32_e32 v128, 0
	v_mov_b32_e32 v129, 0
	v_mov_b32_e32 v130, 0
	v_mov_b32_e32 v131, 0
	s_and_saveexec_b64 s[36:37], s[6:7]
	s_cbranch_execz .Lp2_gfrag_done
	ds_read_b128 v[60:63], v96
	ds_read_b128 v[64:67], v96 offset:16
	ds_read_b128 v[68:71], v96 offset:1024
	ds_read_b128 v[72:75], v96 offset:1040
	ds_read_b128 v[170:173], v96 offset:2048
	ds_read_b128 v[174:177], v96 offset:2064
	ds_read_b128 v[178:181], v96 offset:3072
	ds_read_b128 v[182:185], v96 offset:3088
	s_waitcnt lgkmcnt(6)
	v_cvt_pk_bf16_f32 v104, v60, v61
	v_cvt_pk_bf16_f32 v105, v62, v63
	v_cvt_pk_bf16_f32 v106, v64, v65
	v_cvt_pk_bf16_f32 v107, v66, v67
	v_lshlrev_b32_e32 v132, 16, v104
	v_and_b32_e32 v133, 0xffff0000, v104
	v_lshlrev_b32_e32 v134, 16, v105
	v_and_b32_e32 v135, 0xffff0000, v105
	v_lshlrev_b32_e32 v136, 16, v106
	v_and_b32_e32 v137, 0xffff0000, v106
	v_lshlrev_b32_e32 v138, 16, v107
	v_and_b32_e32 v139, 0xffff0000, v107
	v_pk_add_f32 v[60:61], v[60:61], v[132:133] neg_lo:[0,1] neg_hi:[0,1]
	v_pk_add_f32 v[62:63], v[62:63], v[134:135] neg_lo:[0,1] neg_hi:[0,1]
	v_pk_add_f32 v[64:65], v[64:65], v[136:137] neg_lo:[0,1] neg_hi:[0,1]
	v_pk_add_f32 v[66:67], v[66:67], v[138:139] neg_lo:[0,1] neg_hi:[0,1]
	v_cvt_pk_bf16_f32 v100, v60, v61
	v_cvt_pk_bf16_f32 v101, v62, v63
	v_cvt_pk_bf16_f32 v102, v64, v65
	v_cvt_pk_bf16_f32 v103, v66, v67
	s_waitcnt lgkmcnt(4)
	v_cvt_pk_bf16_f32 v112, v68, v69
	v_cvt_pk_bf16_f32 v113, v70, v71
	v_cvt_pk_bf16_f32 v114, v72, v73
	v_cvt_pk_bf16_f32 v115, v74, v75
	v_lshlrev_b32_e32 v132, 16, v112
	v_and_b32_e32 v133, 0xffff0000, v112
	v_lshlrev_b32_e32 v134, 16, v113
	v_and_b32_e32 v135, 0xffff0000, v113
	v_lshlrev_b32_e32 v136, 16, v114
	v_and_b32_e32 v137, 0xffff0000, v114
	v_lshlrev_b32_e32 v138, 16, v115
	v_and_b32_e32 v139, 0xffff0000, v115
	v_pk_add_f32 v[68:69], v[68:69], v[132:133] neg_lo:[0,1] neg_hi:[0,1]
	v_pk_add_f32 v[70:71], v[70:71], v[134:135] neg_lo:[0,1] neg_hi:[0,1]
	v_pk_add_f32 v[72:73], v[72:73], v[136:137] neg_lo:[0,1] neg_hi:[0,1]
	v_pk_add_f32 v[74:75], v[74:75], v[138:139] neg_lo:[0,1] neg_hi:[0,1]
	v_cvt_pk_bf16_f32 v108, v68, v69
	v_cvt_pk_bf16_f32 v109, v70, v71
	v_cvt_pk_bf16_f32 v110, v72, v73
	v_cvt_pk_bf16_f32 v111, v74, v75
	s_waitcnt lgkmcnt(2)
	v_cvt_pk_bf16_f32 v120, v170, v171
	v_cvt_pk_bf16_f32 v121, v172, v173
	v_cvt_pk_bf16_f32 v122, v174, v175
	v_cvt_pk_bf16_f32 v123, v176, v177
	v_lshlrev_b32_e32 v132, 16, v120
	v_and_b32_e32 v133, 0xffff0000, v120
	v_lshlrev_b32_e32 v134, 16, v121
	v_and_b32_e32 v135, 0xffff0000, v121
	v_lshlrev_b32_e32 v136, 16, v122
	v_and_b32_e32 v137, 0xffff0000, v122
	v_lshlrev_b32_e32 v138, 16, v123
	v_and_b32_e32 v139, 0xffff0000, v123
	v_pk_add_f32 v[170:171], v[170:171], v[132:133] neg_lo:[0,1] neg_hi:[0,1]
	v_pk_add_f32 v[172:173], v[172:173], v[134:135] neg_lo:[0,1] neg_hi:[0,1]
	v_pk_add_f32 v[174:175], v[174:175], v[136:137] neg_lo:[0,1] neg_hi:[0,1]
	v_pk_add_f32 v[176:177], v[176:177], v[138:139] neg_lo:[0,1] neg_hi:[0,1]
	v_cvt_pk_bf16_f32 v116, v170, v171
	v_cvt_pk_bf16_f32 v117, v172, v173
	v_cvt_pk_bf16_f32 v118, v174, v175
	v_cvt_pk_bf16_f32 v119, v176, v177
	s_waitcnt lgkmcnt(0)
	v_cvt_pk_bf16_f32 v128, v178, v179
	v_cvt_pk_bf16_f32 v129, v180, v181
	v_cvt_pk_bf16_f32 v130, v182, v183
	v_cvt_pk_bf16_f32 v131, v184, v185
	v_lshlrev_b32_e32 v132, 16, v128
	v_and_b32_e32 v133, 0xffff0000, v128
	v_lshlrev_b32_e32 v134, 16, v129
	v_and_b32_e32 v135, 0xffff0000, v129
	v_lshlrev_b32_e32 v136, 16, v130
	v_and_b32_e32 v137, 0xffff0000, v130
	v_lshlrev_b32_e32 v138, 16, v131
	v_and_b32_e32 v139, 0xffff0000, v131
	v_pk_add_f32 v[178:179], v[178:179], v[132:133] neg_lo:[0,1] neg_hi:[0,1]
	v_pk_add_f32 v[180:181], v[180:181], v[134:135] neg_lo:[0,1] neg_hi:[0,1]
	v_pk_add_f32 v[182:183], v[182:183], v[136:137] neg_lo:[0,1] neg_hi:[0,1]
	v_pk_add_f32 v[184:185], v[184:185], v[138:139] neg_lo:[0,1] neg_hi:[0,1]
	v_cvt_pk_bf16_f32 v124, v178, v179
	v_cvt_pk_bf16_f32 v125, v180, v181
	v_cvt_pk_bf16_f32 v126, v182, v183
	v_cvt_pk_bf16_f32 v127, v184, v185

; #define LAS __attribute__((address_space(3)))
; __device__ __forceinline__ void phase_gla_pre(const Params& P, LAS unsigned char* lds, bool dry) {
;     ...
;         for (int tt = 0; tt < 4; ++tt) {
;             bf16x8 ahi = (bf16x8){0, 0, 0, 0, 0, 0, 0, 0}, alo = ahi;
;             if (g < 2) { const f32x4 l0 = *(const LAS f32x4*)(Llr + (16 * tt + fr) * 16 + 8 * g), l1 = *(const LAS f32x4*)(Llr + (16 * tt + fr) * 16 + 8 * g + 4); split8(l0, l1, ahi, alo); }
;             f32x4 acc = (f32x4){bg, bg, bg, bg};
;             acc = __builtin_amdgcn_mfma_f32_16x16x32_bf16(alo, bhi, acc, 0, 0, 0); acc = __builtin_amdgcn_mfma_f32_16x16x32_bf16(ahi, blo, acc, 0, 0, 0); acc = __builtin_amdgcn_mfma_f32_16x16x32_bf16(ahi, bhi, acc, 0, 0, 0);
;             float pr[4];
; #pragma unroll
;             for (int r = 0; r < 4; ++r) { const float lg = acc[r]; const float ls = fminf(lg, 0.f) - __logf(1.0f + __expf(-fabsf(lg))); pr[r] = ls * (1.0f / 16.0f) + (r ? pr[r - 1] : 0.f); }
;             const float T = pr[3];
.Lp2_nowait1:
	v_mov_b32_e32 v140, v20
	v_mov_b32_e32 v141, v21
	v_mov_b32_e32 v142, v22
	v_mov_b32_e32 v143, v23
	v_mov_b32_e32 v144, v24
	v_mov_b32_e32 v145, v25
	v_mov_b32_e32 v146, v26
	v_mov_b32_e32 v147, v27
	v_mov_b32_e32 v148, v28
	s_and_b32 s98, s38, 0xff
	s_cselect_b32 s98, 0, 1
	v_mov_b32_e32 v29, v28
	v_mov_b32_e32 v30, v28
	v_mov_b32_e32 v31, v28
	s_nop 1
	v_mfma_f32_16x16x32_bf16 v[32:35], v[100:103], v[20:23], v[28:31]
	v_mfma_f32_16x16x32_bf16 v[36:39], v[108:111], v[20:23], v[28:31]
	v_mfma_f32_16x16x32_bf16 v[40:43], v[116:119], v[20:23], v[28:31]
	v_mfma_f32_16x16x32_bf16 v[44:47], v[124:127], v[20:23], v[28:31]
	v_mfma_f32_16x16x32_bf16 v[32:35], v[104:107], v[24:27], v[32:35]
	v_mfma_f32_16x16x32_bf16 v[36:39], v[112:115], v[24:27], v[36:39]
	v_mfma_f32_16x16x32_bf16 v[40:43], v[120:123], v[24:27], v[40:43]
	v_mfma_f32_16x16x32_bf16 v[44:47], v[128:131], v[24:27], v[44:47]
	v_mfma_f32_16x16x32_bf16 v[32:35], v[104:107], v[20:23], v[32:35]
	v_mfma_f32_16x16x32_bf16 v[36:39], v[112:115], v[20:23], v[36:39]
	v_mfma_f32_16x16x32_bf16 v[40:43], v[120:123], v[20:23], v[40:43]
	v_mfma_f32_16x16x32_bf16 v[44:47], v[128:131], v[20:23], v[44:47]
	s_nop 7
	v_min_f32_e32 v186, 0, v32
	v_min_f32_e32 v187, 0, v36
	v_min_f32_e32 v188, 0, v40
	v_min_f32_e32 v189, 0, v44
	v_mul_f32_e64 v190, |v32|, s89
	v_mul_f32_e64 v191, |v36|, s89
	v_mul_f32_e64 v192, |v40|, s89
	v_mul_f32_e64 v193, |v44|, s89
	v_exp_f32_e32 v190, v190
	v_exp_f32_e32 v191, v191
	v_exp_f32_e32 v192, v192
	v_exp_f32_e32 v193, v193
	v_add_f32_e32 v190, 1.0, v190
	v_add_f32_e32 v191, 1.0, v191
	v_add_f32_e32 v192, 1.0, v192
	v_add_f32_e32 v193, 1.0, v193
	v_log_f32_e32 v190, v190
	v_log_f32_e32 v191, v191
	v_log_f32_e32 v192, v192
	v_log_f32_e32 v193, v193
	v_mul_f32_e32 v196, 0x3f317217, v190
	v_mul_f32_e32 v197, 0x3f317217, v191
	v_mul_f32_e32 v198, 0x3f317217, v192
	v_mul_f32_e32 v199, 0x3f317217, v193
	v_fma_f32 v196, v190, s91, -v196
	v_fma_f32 v197, v191, s91, -v197
	v_fma_f32 v198, v192, s91, -v198
	v_fma_f32 v199, v193, s91, -v199
	v_fmac_f32_e32 v196, 0x3377d1cf, v190
	v_fmac_f32_e32 v197, 0x3377d1cf, v191
	v_fmac_f32_e32 v198, 0x3377d1cf, v192
	v_fmac_f32_e32 v199, 0x3377d1cf, v193
	v_fmac_f32_e32 v196, 0x3f317217, v190
	v_fmac_f32_e32 v197, 0x3f317217, v191
	v_fmac_f32_e32 v198, 0x3f317217, v192
	v_fmac_f32_e32 v199, 0x3f317217, v193
	v_sub_f32_e32 v186, v186, v196
	v_sub_f32_e32 v187, v187, v197
	v_sub_f32_e32 v188, v188, v198
	v_sub_f32_e32 v189, v189, v199
	v_fma_f32 v32, v186, s93, 0
	v_fma_f32 v36, v187, s93, 0
	v_fma_f32 v40, v188, s93, 0
	v_fma_f32 v44, v189, s93, 0
	v_min_f32_e32 v186, 0, v33
	v_min_f32_e32 v187, 0, v37
	v_min_f32_e32 v188, 0, v41
	v_min_f32_e32 v189, 0, v45
	v_mul_f32_e64 v190, |v33|, s89
	v_mul_f32_e64 v191, |v37|, s89
	v_mul_f32_e64 v192, |v41|, s89
	v_mul_f32_e64 v193, |v45|, s89
	v_exp_f32_e32 v190, v190
	v_exp_f32_e32 v191, v191
	v_exp_f32_e32 v192, v192
	v_exp_f32_e32 v193, v193
	v_add_f32_e32 v190, 1.0, v190
	v_add_f32_e32 v191, 1.0, v191
	v_add_f32_e32 v192, 1.0, v192
	v_add_f32_e32 v193, 1.0, v193
	v_log_f32_e32 v190, v190
	v_log_f32_e32 v191, v191
	v_log_f32_e32 v192, v192
	v_log_f32_e32 v193, v193
	v_mul_f32_e32 v196, 0x3f317217, v190
	v_mul_f32_e32 v197, 0x3f317217, v191
	v_mul_f32_e32 v198, 0x3f317217, v192
	v_mul_f32_e32 v199, 0x3f317217, v193
	v_fma_f32 v196, v190, s91, -v196
	v_fma_f32 v197, v191, s91, -v197
	v_fma_f32 v198, v192, s91, -v198
	v_fma_f32 v199, v193, s91, -v199
	v_fmac_f32_e32 v196, 0x3377d1cf, v190
	v_fmac_f32_e32 v197, 0x3377d1cf, v191
	v_fmac_f32_e32 v198, 0x3377d1cf, v192
	v_fmac_f32_e32 v199, 0x3377d1cf, v193
	v_fmac_f32_e32 v196, 0x3f317217, v190
	v_fmac_f32_e32 v197, 0x3f317217, v191
	v_fmac_f32_e32 v198, 0x3f317217, v192
	v_fmac_f32_e32 v199, 0x3f317217, v193
	v_sub_f32_e32 v186, v186, v196
	v_sub_f32_e32 v187, v187, v197
	v_sub_f32_e32 v188, v188, v198
	v_sub_f32_e32 v189, v189, v199
	v_fmamk_f32 v33, v186, 0x3d800000, v32
	v_fmamk_f32 v37, v187, 0x3d800000, v36
	v_fmamk_f32 v41, v188, 0x3d800000, v40
	v_fmamk_f32 v45, v189, 0x3d800000, v44
	v_min_f32_e32 v186, 0, v34
	v_min_f32_e32 v187, 0, v38
	v_min_f32_e32 v188, 0, v42
	v_min_f32_e32 v189, 0, v46
	v_mul_f32_e64 v190, |v34|, s89
	v_mul_f32_e64 v191, |v38|, s89
	v_mul_f32_e64 v192, |v42|, s89
	v_mul_f32_e64 v193, |v46|, s89
	v_exp_f32_e32 v190, v190
	v_exp_f32_e32 v191, v191
	v_exp_f32_e32 v192, v192
	v_exp_f32_e32 v193, v193
	v_add_f32_e32 v190, 1.0, v190
	v_add_f32_e32 v191, 1.0, v191
	v_add_f32_e32 v192, 1.0, v192
	v_add_f32_e32 v193, 1.0, v193
	v_log_f32_e32 v190, v190
	v_log_f32_e32 v191, v191
	v_log_f32_e32 v192, v192
	v_log_f32_e32 v193, v193
	v_mul_f32_e32 v196, 0x3f317217, v190
	v_mul_f32_e32 v197, 0x3f317217, v191
	v_mul_f32_e32 v198, 0x3f317217, v192
	v_mul_f32_e32 v199, 0x3f317217, v193
	v_fma_f32 v196, v190, s91, -v196
	v_fma_f32 v197, v191, s91, -v197
	v_fma_f32 v198, v192, s91, -v198
	v_fma_f32 v199, v193, s91, -v199
	v_fmac_f32_e32 v196, 0x3377d1cf, v190
	v_fmac_f32_e32 v197, 0x3377d1cf, v191
	v_fmac_f32_e32 v198, 0x3377d1cf, v192
	v_fmac_f32_e32 v199, 0x3377d1cf, v193
	v_fmac_f32_e32 v196, 0x3f317217, v190
	v_fmac_f32_e32 v197, 0x3f317217, v191
	v_fmac_f32_e32 v198, 0x3f317217, v192
	v_fmac_f32_e32 v199, 0x3f317217, v193
	v_sub_f32_e32 v186, v186, v196
	v_sub_f32_e32 v187, v187, v197
	v_sub_f32_e32 v188, v188, v198
	v_sub_f32_e32 v189, v189, v199
	v_fmamk_f32 v34, v186, 0x3d800000, v33
	v_fmamk_f32 v38, v187, 0x3d800000, v37
	v_fmamk_f32 v42, v188, 0x3d800000, v41
	v_fmamk_f32 v46, v189, 0x3d800000, v45
	v_min_f32_e32 v186, 0, v35
	v_min_f32_e32 v187, 0, v39
	v_min_f32_e32 v188, 0, v43
	v_min_f32_e32 v189, 0, v47
; #define LAS __attribute__((address_space(3)))
; __device__ __forceinline__ void phase_gla_pre(const Params& P, LAS unsigned char* lds, bool dry) {
;     ...
;             for (int r = 0; r < 4; ++r) { const float lg = acc[r]; const float ls = fminf(lg, 0.f) - __logf(1.0f + __expf(-fabsf(lg))); pr[r] = ls * (1.0f / 16.0f) + (r ? pr[r - 1] : 0.f); }
;             const float T = pr[3];
;             const float u1 = __shfl_up(T, 16), s1 = T + (g >= 1 ? u1 : 0.f);
;             const float u2 = __shfl_up(s1, 32), s2 = s1 + (g >= 2 ? u2 : 0.f);
;             const float base = run + (s2 - T); run += __shfl(s2, 48 + fr);
; #pragma unroll
;             for (int r = 0; r < 4; ++r) *(LAS float*)(Lb + (16 * tt + 4 * g + r) * BP + (16 * w + fr) * 4) = base + pr[r];
;         }
	v_mul_f32_e64 v190, |v35|, s89
	v_mul_f32_e64 v191, |v39|, s89
	v_mul_f32_e64 v192, |v43|, s89
	v_mul_f32_e64 v193, |v47|, s89
	v_exp_f32_e32 v190, v190
	v_exp_f32_e32 v191, v191
	v_exp_f32_e32 v192, v192
	v_exp_f32_e32 v193, v193
	v_add_f32_e32 v190, 1.0, v190
	v_add_f32_e32 v191, 1.0, v191
	v_add_f32_e32 v192, 1.0, v192
	v_add_f32_e32 v193, 1.0, v193
	v_log_f32_e32 v190, v190
	v_log_f32_e32 v191, v191
	v_log_f32_e32 v192, v192
	v_log_f32_e32 v193, v193
	v_mul_f32_e32 v196, 0x3f317217, v190
	v_mul_f32_e32 v197, 0x3f317217, v191
	v_mul_f32_e32 v198, 0x3f317217, v192
	v_mul_f32_e32 v199, 0x3f317217, v193
	v_fma_f32 v196, v190, s91, -v196
	v_fma_f32 v197, v191, s91, -v197
	v_fma_f32 v198, v192, s91, -v198
	v_fma_f32 v199, v193, s91, -v199
	v_fmac_f32_e32 v196, 0x3377d1cf, v190
	v_fmac_f32_e32 v197, 0x3377d1cf, v191
	v_fmac_f32_e32 v198, 0x3377d1cf, v192
	v_fmac_f32_e32 v199, 0x3377d1cf, v193
	v_fmac_f32_e32 v196, 0x3f317217, v190
	v_fmac_f32_e32 v197, 0x3f317217, v191
	v_fmac_f32_e32 v198, 0x3f317217, v192
	v_fmac_f32_e32 v199, 0x3f317217, v193
	v_sub_f32_e32 v186, v186, v196
	v_sub_f32_e32 v187, v187, v197
	v_sub_f32_e32 v188, v188, v198
	v_sub_f32_e32 v189, v189, v199
	v_fmamk_f32 v35, v186, 0x3d800000, v34
	v_fmamk_f32 v39, v187, 0x3d800000, v38
	v_fmamk_f32 v43, v188, 0x3d800000, v42
	v_fmamk_f32 v47, v189, 0x3d800000, v46
	ds_bpermute_b32 v200, v83, v35
	ds_bpermute_b32 v201, v83, v39
	ds_bpermute_b32 v202, v83, v43
	ds_bpermute_b32 v203, v83, v47
	s_waitcnt lgkmcnt(0)
	v_cndmask_b32_e64 v200, v200, 0, s[8:9]
	v_cndmask_b32_e64 v201, v201, 0, s[8:9]
	v_cndmask_b32_e64 v202, v202, 0, s[8:9]
	v_cndmask_b32_e64 v203, v203, 0, s[8:9]
	v_add_f32_e32 v186, v200, v35
	v_add_f32_e32 v187, v201, v39
	v_add_f32_e32 v188, v202, v43
	v_add_f32_e32 v189, v203, v47
	ds_bpermute_b32 v190, v84, v186
	ds_bpermute_b32 v191, v84, v187
	ds_bpermute_b32 v192, v84, v188
	ds_bpermute_b32 v193, v84, v189
	s_waitcnt lgkmcnt(0)
	v_cndmask_b32_e64 v190, 0, v190, s[10:11]
	v_cndmask_b32_e64 v191, 0, v191, s[10:11]
	v_cndmask_b32_e64 v192, 0, v192, s[10:11]
	v_cndmask_b32_e64 v193, 0, v193, s[10:11]
	v_add_f32_e32 v196, v190, v186
	v_add_f32_e32 v197, v191, v187
	v_add_f32_e32 v198, v192, v188
	v_add_f32_e32 v199, v193, v189
	ds_bpermute_b32 v204, v85, v196
	ds_bpermute_b32 v205, v85, v197
	ds_bpermute_b32 v206, v85, v198
	v_sub_f32_e32 v200, v196, v35
	v_sub_f32_e32 v201, v197, v39
	v_sub_f32_e32 v202, v198, v43
	v_sub_f32_e32 v203, v199, v47
	v_add_f32_e32 v212, 0, v200
	v_add_f32_e32 v220, v32, v212
	v_add_f32_e32 v221, v33, v212
	v_add_u32_e32 v222, 0x8800, v98
	ds_write2_b32 v222, v220, v221 offset1:132
	v_add_f32_e32 v224, v34, v212
	v_add_f32_e32 v225, v35, v212
	v_add_u32_e32 v226, 0x8c00, v98
	ds_write2_b32 v226, v224, v225 offset0:8 offset1:140
	s_waitcnt lgkmcnt(4)
	v_add_f32_e32 v208, 0, v204
	v_add_f32_e32 v213, v208, v201
	v_add_f32_e32 v220, v36, v213
	v_add_f32_e32 v221, v37, v213
	v_add_u32_e32 v222, 0xa800, v98
	ds_write2_b32 v222, v220, v221 offset0:64 offset1:196
	v_add_f32_e32 v224, v38, v213
	v_add_f32_e32 v225, v39, v213
	v_add_u32_e32 v226, 0xac00, v98
	ds_write2_b32 v226, v224, v225 offset0:72 offset1:204
	s_waitcnt lgkmcnt(5)
	v_add_f32_e32 v209, v208, v205
	v_add_f32_e32 v214, v209, v202
	v_add_f32_e32 v220, v40, v214
	v_add_f32_e32 v221, v41, v214
	v_add_u32_e32 v222, 0xca00, v98
	ds_write2_b32 v222, v220, v221 offset1:132
	v_add_f32_e32 v224, v42, v214
	v_add_f32_e32 v225, v43, v214
	v_add_u32_e32 v226, 0xce00, v98
	ds_write2_b32 v226, v224, v225 offset0:8 offset1:140
	s_waitcnt lgkmcnt(6)
	v_add_f32_e32 v210, v209, v206
	v_add_f32_e32 v216, v210, v203
	v_add_f32_e32 v220, v44, v216
	v_add_f32_e32 v221, v45, v216
	v_add_u32_e32 v222, 0xea00, v98
	ds_write2_b32 v222, v220, v221 offset0:64 offset1:196
	v_add_f32_e32 v224, v46, v216
	v_add_f32_e32 v225, v47, v216
	v_add_u32_e32 v226, 0xee00, v98
	ds_write2_b32 v226, v224, v225 offset0:72 offset1:204
	v_and_b32_e32 v111, 0xffff0000, v5
	v_and_b32_e32 v110, 0xffff0000, v4
	v_and_b32_e32 v117, 0xffff0000, v13
	v_and_b32_e32 v116, 0xffff0000, v12
	v_and_b32_e32 v121, 0xffff0000, v7
	v_and_b32_e32 v120, 0xffff0000, v6
	v_and_b32_e32 v127, 0xffff0000, v17
	v_and_b32_e32 v126, 0xffff0000, v16
	v_lshlrev_b32_e32 v125, 16, v17
	v_lshlrev_b32_e32 v124, 16, v16
	v_lshlrev_b32_e32 v133, 16, v11
	v_lshlrev_b32_e32 v132, 16, v10
	v_and_b32_e32 v135, 0xffff0000, v11
	v_and_b32_e32 v134, 0xffff0000, v10
	s_and_b32 s74, s1, 0xfc0
	s_ashr_i32 s83, s82, 31
	s_lshl_b64 s[36:37], s[82:83], 20
	v_add_u32_e32 v22, s94, v87
	s_waitcnt lgkmcnt(0)
	s_barrier
; #define LAS __attribute__((address_space(3)))
; __device__ __forceinline__ float bflo(unsigned w) { return __uint_as_float(w << 16); }
; __device__ __forceinline__ float bfhi(unsigned w) { return __uint_as_float(w & 0xffff0000u); }
; __device__ __forceinline__ void phase_gla_pre(const Params& P, LAS unsigned char* lds, bool dry) {
;     ...
;         __syncthreads();
;         {
;             f32x4 bb[4], bm[4], bl[4];
; #pragma unroll
;             for (int i = 0; i < 4; ++i) { bb[i] = *(const LAS f32x4*)(Lb + te * BP + (16 * kc + 4 * i) * 4); bm[i] = *(const LAS f32x4*)(Lb + 31 * BP + (16 * kc + 4 * i) * 4); bl[i] = *(const LAS f32x4*)(Lb + 63 * BP + (16 * kc + 4 * i) * 4); }
;             unsigned oqi[8], oki[8], oqd[8], oks[8];
; #pragma unroll
;             for (int e2 = 0; e2 < 8; ++e2) {
;                 const unsigned qw = e2 < 4 ? rq[0][e2] : rq[1][e2 - 4], kw = e2 < 4 ? rk[0][e2] : rk[1][e2 - 4];
;                 float vqi[2], vki[2], vqd[2], vks[2];
; #pragma unroll
;                 for (int hh = 0; hh < 2; ++hh) {
;                     const int e = 2 * e2 + hh; const float bv = bb[e >> 2][e & 3], bmv = bm[e >> 2][e & 3], blv = bl[e >> 2][e & 3];
;                     const float qv = hh ? bfhi(qw) : bflo(qw), kv = hh ? bfhi(kw) : bflo(kw);
;                     const float e1 = __expf(bv - bmv);
;                     vqi[hh] = qv * e1; vki[hh] = kv * __builtin_amdgcn_rcpf(e1); vqd[hh] = qv * __expf(bv); vks[hh] = kv * __expf(blv - bv);
	v_add_u32_e32 v20, v86, v87
	v_add_u32_e32 v21, 0, v87
	ds_read_b128 v[32:35], v22
	ds_read_b128 v[24:27], v89
	ds_read_b128 v[60:63], v21 offset:51184
	ds_read_b128 v[64:67], v20 offset:34816
	ds_read_b128 v[74:77], v20 offset:34832
	ds_read_b128 v[44:47], v20 offset:34848
	ds_read_b128 v[36:39], v20 offset:34864
	ds_read_b128 v[100:103], v21 offset:51200
	s_waitcnt lgkmcnt(4)
	v_sub_f32_e32 v61, v65, v61
	v_mul_f32_e32 v61, 0x3fb8aa3b, v61
	v_sub_f32_e32 v63, v67, v63
	v_exp_f32_e32 v72, v61
	v_sub_f32_e32 v61, v32, v64
	v_mul_f32_e32 v63, 0x3fb8aa3b, v63
	v_mul_f32_e32 v61, 0x3fb8aa3b, v61
	v_exp_f32_e32 v73, v63
	v_exp_f32_e32 v78, v61
	v_mul_f32_e32 v61, 0x3fb8aa3b, v65
	v_sub_f32_e32 v20, v64, v60
	v_exp_f32_e32 v108, v61
	v_sub_f32_e32 v61, v66, v62
	v_mul_f32_e32 v20, 0x3fb8aa3b, v20
	v_mul_f32_e32 v69, 0x3fb8aa3b, v64
	v_mul_f32_e32 v61, 0x3fb8aa3b, v61
	v_sub_f32_e32 v62, v33, v65
	v_mul_f32_e32 v65, 0x3fb8aa3b, v66
	v_sub_f32_e32 v63, v34, v66
	v_exp_f32_e32 v60, v20
	v_exp_f32_e32 v70, v69
	v_rcp_f32_e32 v64, v72
	v_exp_f32_e32 v61, v61
	v_exp_f32_e32 v71, v65
	v_mul_f32_e32 v63, 0x3fb8aa3b, v63
	v_rcp_f32_e32 v65, v73
	v_exp_f32_e32 v79, v63
	v_mul_f32_e32 v63, 0x3fb8aa3b, v67
	v_exp_f32_e32 v109, v63
	v_sub_f32_e32 v63, v35, v67
	v_lshlrev_b32_e32 v67, 16, v5
	v_lshlrev_b32_e32 v66, 16, v4
	v_pk_mul_f32 v[112:113], v[60:61], v[66:67]
	v_pk_mul_f32 v[114:115], v[72:73], v[110:111]
	v_pk_mul_f32 v[72:73], v[64:65], v[116:117]
	v_pk_mul_f32 v[64:65], v[70:71], v[66:67]
	s_waitcnt lgkmcnt(0)
	v_sub_f32_e32 v66, v74, v100
	v_mul_f32_e32 v66, 0x3fb8aa3b, v66
	v_mul_f32_e32 v71, 0x3fb8aa3b, v74
	v_exp_f32_e32 v70, v66
	v_pk_mul_f32 v[66:67], v[108:109], v[110:111]
	v_exp_f32_e32 v108, v71
	v_sub_f32_e32 v71, v75, v101
	v_mul_f32_e32 v71, 0x3fb8aa3b, v71
	v_mul_f32_e32 v62, 0x3fb8aa3b, v62
	v_mul_f32_e32 v63, 0x3fb8aa3b, v63
	v_exp_f32_e32 v100, v71
	v_sub_f32_e32 v71, v24, v74
	v_exp_f32_e32 v62, v62
	v_exp_f32_e32 v63, v63
	v_mul_f32_e32 v71, 0x3fb8aa3b, v71
	v_exp_f32_e32 v74, v71
	v_mul_f32_e32 v71, 0x3fb8aa3b, v75
	v_sub_f32_e32 v75, v25, v75
	v_mul_f32_e32 v75, 0x3fb8aa3b, v75
	v_exp_f32_e32 v118, v75
	v_mul_f32_e32 v75, 0x3fb8aa3b, v76
	v_pk_mul_f32 v[62:63], v[62:63], v[116:117]
	v_exp_f32_e32 v116, v71
	v_sub_f32_e32 v71, v76, v102
	v_exp_f32_e32 v109, v75
	v_sub_f32_e32 v75, v77, v103
	v_mul_f32_e32 v71, 0x3fb8aa3b, v71
	v_mul_f32_e32 v75, 0x3fb8aa3b, v75
	v_rcp_f32_e32 v68, v60
	v_rcp_f32_e32 v69, v61
	v_exp_f32_e32 v71, v71
	v_exp_f32_e32 v101, v75
	v_sub_f32_e32 v75, v26, v76
	v_mul_f32_e32 v76, 0x3fb8aa3b, v77
	v_exp_f32_e32 v117, v76
	v_sub_f32_e32 v76, v27, v77
	v_mul_f32_e32 v76, 0x3fb8aa3b, v76
	v_lshlrev_b32_e32 v61, 16, v13
	v_lshlrev_b32_e32 v60, 16, v12
	v_exp_f32_e32 v119, v76
	v_lshlrev_b32_e32 v77, 16, v7
	v_lshlrev_b32_e32 v76, 16, v6
	v_pk_mul_f32 v[68:69], v[68:69], v[60:61]
	v_pk_mul_f32 v[60:61], v[78:79], v[60:61]
	v_rcp_f32_e32 v78, v70
	v_rcp_f32_e32 v110, v100
	v_rcp_f32_e32 v79, v71
	v_rcp_f32_e32 v111, v101
	v_pk_mul_f32 v[70:71], v[70:71], v[76:77]
	v_pk_mul_f32 v[100:101], v[100:101], v[120:121]
	v_cvt_pk_bf16_f32 v224, v112, v114
	v_cvt_pk_bf16_f32 v222, v113, v115
	v_cvt_pk_bf16_f32 v221, v70, v100
	v_cvt_pk_bf16_f32 v220, v71, v101
	ds_read_b128 v[104:107], v21 offset:51216
	ds_read_b128 v[40:43], v21 offset:51232
	ds_read_b128 v[28:31], v90
	ds_read_b128 v[20:23], v91
	v_mov_b32_e32 v103, v220
	v_mov_b32_e32 v102, v221
	v_lshlrev_b32_e32 v71, 16, v15
	v_lshlrev_b32_e32 v70, 16, v14
	v_mul_f32_e32 v75, 0x3fb8aa3b, v75
	v_mov_b32_e32 v101, v222
	v_mov_b32_e32 v100, v224
	v_pk_mul_f32 v[114:115], v[78:79], v[70:71]
	s_waitcnt lgkmcnt(3)
	v_sub_f32_e32 v78, v44, v104
	v_sub_f32_e32 v105, v45, v105
	v_exp_f32_e32 v75, v75
	v_mul_f32_e32 v78, 0x3fb8aa3b, v78
	v_mul_f32_e32 v105, 0x3fb8aa3b, v105
	v_exp_f32_e32 v104, v78
	v_pk_mul_f32 v[78:79], v[116:117], v[120:121]
	v_exp_f32_e32 v116, v105
	v_mul_f32_e32 v105, 0x3fb8aa3b, v45
	s_waitcnt lgkmcnt(1)
	v_sub_f32_e32 v45, v29, v45
	v_mul_f32_e32 v45, 0x3fb8aa3b, v45
	v_and_b32_e32 v113, 0xffff0000, v15
	v_and_b32_e32 v112, 0xffff0000, v14
	v_exp_f32_e32 v120, v105
	v_sub_f32_e32 v105, v46, v106
	v_exp_f32_e32 v106, v45
	v_mul_f32_e32 v45, 0x3fb8aa3b, v46
	v_pk_mul_f32 v[110:111], v[110:111], v[112:113]
	v_pk_mul_f32 v[70:71], v[74:75], v[70:71]
	v_pk_mul_f32 v[74:75], v[118:119], v[112:113]
	v_exp_f32_e32 v113, v45
	v_sub_f32_e32 v45, v47, v107
	v_mul_f32_e32 v45, 0x3fb8aa3b, v45
	v_exp_f32_e32 v117, v45
	v_sub_f32_e32 v45, v30, v46
	v_mul_f32_e32 v46, 0x3fb8aa3b, v47
	v_exp_f32_e32 v121, v46
	v_sub_f32_e32 v46, v31, v47
	v_pk_mul_f32 v[76:77], v[108:109], v[76:77]
	v_mul_f32_e32 v109, 0x3fb8aa3b, v44
	v_mul_f32_e32 v105, 0x3fb8aa3b, v105
	v_mul_f32_e32 v46, 0x3fb8aa3b, v46
	v_exp_f32_e32 v112, v109
	v_exp_f32_e32 v105, v105
	v_exp_f32_e32 v107, v46
	v_rcp_f32_e32 v118, v116
	v_rcp_f32_e32 v119, v117
	v_sub_f32_e32 v44, v28, v44
	v_lshlrev_b32_e32 v47, 16, v9
	v_lshlrev_b32_e32 v46, 16, v8
	v_rcp_f32_e32 v108, v104
	v_mul_f32_e32 v44, 0x3fb8aa3b, v44
	v_rcp_f32_e32 v109, v105
	v_mul_f32_e32 v45, 0x3fb8aa3b, v45
	v_pk_mul_f32 v[104:105], v[104:105], v[46:47]
	v_pk_mul_f32 v[112:113], v[112:113], v[46:47]
	v_sub_f32_e32 v40, v36, v40
	v_pk_mul_f32 v[46:47], v[106:107], v[126:127]
	v_mul_f32_e32 v107, 0x3fb8aa3b, v36
	s_waitcnt lgkmcnt(0)
; #define LAS __attribute__((address_space(3)))
; __device__ __forceinline__ float bflo(unsigned w) { return __uint_as_float(w << 16); }
; __device__ __forceinline__ float bfhi(unsigned w) { return __uint_as_float(w & 0xffff0000u); }
; __device__ __forceinline__ unsigned pk2(float lo, float hi) { return f2bf(lo) | (f2bf(hi) << 16); }
; __device__ __forceinline__ void phase_gla_pre(const Params& P, LAS unsigned char* lds, bool dry) {
;     ...
;                     const int e = 2 * e2 + hh; const float bv = bb[e >> 2][e & 3], bmv = bm[e >> 2][e & 3], blv = bl[e >> 2][e & 3];
;                     const float qv = hh ? bfhi(qw) : bflo(qw), kv = hh ? bfhi(kw) : bflo(kw);
;                     const float e1 = __expf(bv - bmv);
;                     vqi[hh] = qv * e1; vki[hh] = kv * __builtin_amdgcn_rcpf(e1); vqd[hh] = qv * __expf(bv); vks[hh] = kv * __expf(blv - bv);
;                 }
;                 oqi[e2] = pk2(vqi[0], vqi[1]); oki[e2] = pk2(vki[0], vki[1]); oqd[e2] = pk2(vqd[0], vqd[1]); oks[e2] = pk2(vks[0], vks[1]);
;             }
;             *(LAS u32x4*)(Lqi + te * QP + 32 * kc) = (u32x4){oqi[0], oqi[1], oqi[2], oqi[3]}; *(LAS u32x4*)(Lqi + te * QP + 32 * kc + 16) = (u32x4){oqi[4], oqi[5], oqi[6], oqi[7]};
;             *(LAS u32x4*)(Lki + te * QP + 32 * kc) = (u32x4){oki[0], oki[1], oki[2], oki[3]}; *(LAS u32x4*)(Lki + te * QP + 32 * kc + 16) = (u32x4){oki[4], oki[5], oki[6], oki[7]};
;             if (!dry) {
;                 bf16_t* p_ = PJ + ((size_t)bh * SEQ + c * 64 + te) * 128 + 16 * kc;
;                 *(u32x4*)(p_ + T_Q) = (u32x4){oqd[0], oqd[1], oqd[2], oqd[3]}; *(u32x4*)(p_ + T_Q + 8) = (u32x4){oqd[4], oqd[5], oqd[6], oqd[7]};
;                 *(u32x4*)(p_ + T_K) = (u32x4){oks[0], oks[1], oks[2], oks[3]}; *(u32x4*)(p_ + T_K + 8) = (u32x4){oks[4], oks[5], oks[6], oks[7]};
;                 if (te == 63) {
; #pragma unroll
;                     for (int i = 0; i < 4; ++i) *(f32x4*)(DEC + (size_t)item * 128 + 16 * kc + 4 * i) = (f32x4){__expf(bl[i][0]), __expf(bl[i][1]), __expf(bl[i][2]), __expf(bl[i][3])};
;                 }
	v_sub_f32_e32 v36, v20, v36
	v_exp_f32_e32 v44, v44
	v_exp_f32_e32 v45, v45
	v_mul_f32_e32 v36, 0x3fb8aa3b, v36
	v_pk_mul_f32 v[118:119], v[118:119], v[126:127]
	v_exp_f32_e32 v126, v36
	v_mul_f32_e32 v36, 0x3fb8aa3b, v37
	v_sub_f32_e32 v41, v37, v41
	v_exp_f32_e32 v130, v36
	v_sub_f32_e32 v36, v38, v42
	v_mul_f32_e32 v41, 0x3fb8aa3b, v41
	v_mul_f32_e32 v36, 0x3fb8aa3b, v36
	v_pk_mul_f32 v[108:109], v[108:109], v[124:125]
	v_pk_mul_f32 v[44:45], v[44:45], v[124:125]
	v_exp_f32_e32 v124, v41
	v_exp_f32_e32 v41, v36
	v_sub_f32_e32 v36, v21, v37
	v_mul_f32_e32 v36, 0x3fb8aa3b, v36
	v_and_b32_e32 v123, 0xffff0000, v9
	v_and_b32_e32 v122, 0xffff0000, v8
	v_exp_f32_e32 v42, v36
	v_mul_f32_e32 v36, 0x3fb8aa3b, v38
	v_pk_mul_f32 v[116:117], v[116:117], v[122:123]
	v_pk_mul_f32 v[120:121], v[120:121], v[122:123]
	v_exp_f32_e32 v123, v36
	v_sub_f32_e32 v36, v39, v43
	v_mul_f32_e32 v36, 0x3fb8aa3b, v36
	v_mul_f32_e32 v40, 0x3fb8aa3b, v40
	v_exp_f32_e32 v125, v36
	v_sub_f32_e32 v36, v22, v38
	v_exp_f32_e32 v40, v40
	v_mul_f32_e32 v36, 0x3fb8aa3b, v36
	v_exp_f32_e32 v127, v36
	v_mul_f32_e32 v36, 0x3fb8aa3b, v39
	v_exp_f32_e32 v131, v36
	v_sub_f32_e32 v36, v23, v39
	v_mul_f32_e32 v36, 0x3fb8aa3b, v36
	v_rcp_f32_e32 v128, v124
	v_rcp_f32_e32 v129, v125
	v_exp_f32_e32 v43, v36
	v_pk_mul_f32 v[36:37], v[40:41], v[132:133]
	v_pk_mul_f32 v[38:39], v[124:125], v[134:135]
	v_rcp_f32_e32 v106, v40
	v_exp_f32_e32 v122, v107
	v_rcp_f32_e32 v107, v41
	v_cvt_pk_bf16_f32 v228, v104, v116
	v_cvt_pk_bf16_f32 v227, v105, v117
	v_cvt_pk_bf16_f32 v226, v36, v38
	v_cvt_pk_bf16_f32 v225, v37, v39
	v_mov_b32_e32 v39, v225
	v_mov_b32_e32 v38, v226
	v_mov_b32_e32 v37, v227
	v_mov_b32_e32 v36, v228
	ds_write_b128 v92, v[100:103]
	ds_write_b128 v92, v[36:39] offset:16
	v_cvt_pk_bf16_f32 v230, v68, v72
	v_cvt_pk_bf16_f32 v229, v69, v73
	v_lshlrev_b32_e32 v41, 16, v19
	v_lshlrev_b32_e32 v40, 16, v18
	v_cvt_pk_bf16_f32 v39, v115, v111
	v_cvt_pk_bf16_f32 v38, v114, v110
	v_mov_b32_e32 v37, v229
	v_mov_b32_e32 v36, v230
	v_and_b32_e32 v105, 0xffff0000, v19
	v_and_b32_e32 v104, 0xffff0000, v18
	v_pk_mul_f32 v[106:107], v[106:107], v[40:41]
	ds_write_b128 v92, v[36:39] offset:17408
	v_pk_mul_f32 v[116:117], v[128:129], v[104:105]
	s_nop 0
	v_cvt_pk_bf16_f32 v39, v107, v117
	v_cvt_pk_bf16_f32 v38, v106, v116
	v_cvt_pk_bf16_f32 v37, v109, v119
	v_cvt_pk_bf16_f32 v36, v108, v118
	ds_write_b128 v92, v[36:39] offset:17424
	v_lshl_add_u64 v[36:37], s[74:75], 0, v[48:49]
	v_lshlrev_b64 v[36:37], 8, v[36:37]
	v_lshl_add_u64 v[38:39], v[52:53], 0, s[36:37]
	v_lshl_add_u64 v[68:69], v[38:39], 0, v[36:37]
	v_cvt_pk_bf16_f32 v232, v64, v66
	v_cvt_pk_bf16_f32 v233, v65, v67
	s_brev_b32 s36, 16
	v_cvt_pk_bf16_f32 v39, v77, v79
	v_mov_b32_e32 v36, v232
	v_add_co_u32_e32 v64, vcc, s36, v68
	v_cvt_pk_bf16_f32 v38, v76, v78
	v_mov_b32_e32 v37, v233
	v_addc_co_u32_e32 v65, vcc, 0, v69, vcc
	v_pk_mul_f32 v[122:123], v[122:123], v[132:133]
	global_store_dwordx4 v[64:65], v[36:39], off
	v_pk_mul_f32 v[124:125], v[130:131], v[134:135]
	s_nop 0
	v_cvt_pk_bf16_f32 v39, v123, v125
	v_cvt_pk_bf16_f32 v38, v122, v124
	v_cvt_pk_bf16_f32 v37, v113, v121
	v_cvt_pk_bf16_f32 v36, v112, v120
	global_store_dwordx4 v[64:65], v[36:39], off offset:16
	s_nop 1
	s_nop 0
	v_cvt_pk_bf16_f32 v234, v60, v62
	v_cvt_pk_bf16_f32 v235, v61, v63
	v_cvt_pk_bf16_f32 v39, v71, v75
	v_mov_b32_e32 v36, v234
	v_add_co_u32_e32 v60, vcc, s95, v68
	v_pk_mul_f32 v[42:43], v[42:43], v[104:105]
	v_cvt_pk_bf16_f32 v38, v70, v74
	v_mov_b32_e32 v37, v235
	v_addc_co_u32_e32 v61, vcc, 0, v69, vcc
	v_pk_mul_f32 v[40:41], v[126:127], v[40:41]
	global_store_dwordx4 v[60:61], v[36:39], off
	s_nop 1
	v_cvt_pk_bf16_f32 v240, v44, v46
	v_cvt_pk_bf16_f32 v239, v45, v47
	v_cvt_pk_bf16_f32 v238, v40, v42
	v_cvt_pk_bf16_f32 v237, v41, v43
	v_mov_b32_e32 v39, v237
	v_mov_b32_e32 v38, v238
	v_mov_b32_e32 v37, v239
	v_mov_b32_e32 v36, v240
	global_store_dwordx4 v[60:61], v[36:39], off offset:16
	s_and_saveexec_b64 s[36:37], s[12:13]
	s_cbranch_execz .LBB0_494
	v_mul_f32_e32 v32, 0x3fb8aa3b, v32
	v_mul_f32_e32 v33, 0x3fb8aa3b, v33
	v_mul_f32_e32 v34, 0x3fb8aa3b, v34
	v_mul_f32_e32 v35, 0x3fb8aa3b, v35
	v_exp_f32_e32 v32, v32
	v_exp_f32_e32 v33, v33
	v_exp_f32_e32 v34, v34
	v_exp_f32_e32 v35, v35
	v_mul_f32_e32 v24, 0x3fb8aa3b, v24
	v_mul_f32_e32 v25, 0x3fb8aa3b, v25
	v_mul_f32_e32 v26, 0x3fb8aa3b, v26
	v_mul_f32_e32 v27, 0x3fb8aa3b, v27
	s_ashr_i32 s81, s80, 31
	v_exp_f32_e32 v24, v24
	v_exp_f32_e32 v25, v25
	v_exp_f32_e32 v26, v26
	v_exp_f32_e32 v27, v27
	v_mul_f32_e32 v28, 0x3fb8aa3b, v28
	v_mul_f32_e32 v29, 0x3fb8aa3b, v29
	v_mul_f32_e32 v30, 0x3fb8aa3b, v30
	v_mul_f32_e32 v31, 0x3fb8aa3b, v31
	s_lshl_b64 s[42:43], s[80:81], 9
	v_exp_f32_e32 v28, v28
	v_exp_f32_e32 v29, v29
	v_exp_f32_e32 v30, v30
	v_exp_f32_e32 v31, v31
	v_mul_f32_e32 v20, 0x3fb8aa3b, v20
	v_mul_f32_e32 v21, 0x3fb8aa3b, v21
	v_mul_f32_e32 v22, 0x3fb8aa3b, v22
	v_mul_f32_e32 v23, 0x3fb8aa3b, v23
	v_lshl_add_u64 v[36:37], v[54:55], 0, s[42:43]
	v_exp_f32_e32 v20, v20
	v_exp_f32_e32 v21, v21
	v_exp_f32_e32 v22, v22
	v_exp_f32_e32 v23, v23
	global_store_dwordx4 v[36:37], v[32:35], off
	global_store_dwordx4 v[36:37], v[24:27], off offset:16
	global_store_dwordx4 v[36:37], v[28:31], off offset:32
	global_store_dwordx4 v[36:37], v[20:23], off offset:48
